# P10 sel_out epilogue: the 34 gate / o_cmp / o_win loads of both tiles issued before the unit's last barrier, chain loads become moves
# speedup vs baseline: 1.0363x; 1.0025x over previous
.LBB0_1261:
	s_or_b64 exec, exec, s[8:9]
	v_mad_i64_i32 v[6:7], s[8:9], v214, s50, v[216:217]
	v_or_b32_e32 v6, v6, v206
	v_lshlrev_b64 v[6:7], 1, v[6:7]
	v_lshl_add_u64 v[10:11], s[24:25], 0, v[6:7]
	v_mov_b64_e32 v[12:13], v[140:141]
	v_lshl_add_u64 v[8:9], s[70:71], 0, v[6:7]
	v_mov_b64_e32 v[14:15], v[156:157]
	v_lshlrev_b64 v[6:7], 11, v[214:215]
	v_lshl_add_u64 v[6:7], s[44:45], 0, v[6:7]
	v_lshl_add_u64 v[6:7], v[216:217], 1, v[6:7]
	v_lshl_add_u64 v[6:7], v[6:7], 0, v[2:3]
	v_lshlrev_b32_e32 v16, 16, v12
	v_and_b32_e32 v17, 0xffff0000, v12
	v_lshlrev_b32_e32 v12, 16, v13
	v_and_b32_e32 v13, 0xffff0000, v13
	v_lshlrev_b32_e32 v50, 16, v14
	v_and_b32_e32 v51, 0xffff0000, v14
	v_lshlrev_b32_e32 v14, 16, v15
	v_and_b32_e32 v15, 0xffff0000, v15
	v_pk_fma_f32 v[16:17], v[34:35], v[4:5], v[16:17] op_sel_hi:[1,0,1]
	v_pk_fma_f32 v[12:13], v[36:37], v[4:5], v[12:13] op_sel_hi:[1,0,1]
	s_nop 0
	v_pk_add_f32 v[12:13], v[12:13], v[14:15]
	v_pk_add_f32 v[14:15], v[16:17], v[50:51]
	s_nop 0
	v_cvt_pk_bf16_f32 v14, v14, v15
	v_cvt_pk_bf16_f32 v15, v12, v13
	global_store_dwordx2 v[6:7], v[14:15], off
	v_mov_b64_e32 v[12:13], v[142:143]
	s_nop 0
	v_mov_b64_e32 v[14:15], v[158:159]
	v_lshlrev_b32_e32 v16, 16, v12
	v_and_b32_e32 v17, 0xffff0000, v12
	v_lshlrev_b32_e32 v12, 16, v13
	v_and_b32_e32 v13, 0xffff0000, v13
	v_lshlrev_b32_e32 v34, 16, v14
	v_and_b32_e32 v35, 0xffff0000, v14
	v_lshlrev_b32_e32 v14, 16, v15
	v_and_b32_e32 v15, 0xffff0000, v15
	v_pk_fma_f32 v[16:17], v[18:19], v[4:5], v[16:17] op_sel_hi:[1,0,1]
	v_pk_fma_f32 v[12:13], v[20:21], v[4:5], v[12:13] op_sel_hi:[1,0,1]
	s_nop 0
	v_pk_add_f32 v[12:13], v[12:13], v[14:15]
	v_pk_add_f32 v[14:15], v[16:17], v[34:35]
	s_nop 0
	v_cvt_pk_bf16_f32 v14, v14, v15
	v_cvt_pk_bf16_f32 v15, v12, v13
	global_store_dwordx2 v[6:7], v[14:15], off offset:64
	v_mov_b64_e32 v[12:13], v[144:145]
	s_nop 0
	v_mov_b64_e32 v[14:15], v[160:161]
	v_lshlrev_b32_e32 v16, 16, v12
	v_and_b32_e32 v17, 0xffff0000, v12
	v_lshlrev_b32_e32 v12, 16, v13
	v_and_b32_e32 v13, 0xffff0000, v13
	v_lshlrev_b32_e32 v18, 16, v14
	v_and_b32_e32 v19, 0xffff0000, v14
	v_lshlrev_b32_e32 v14, 16, v15
	v_and_b32_e32 v15, 0xffff0000, v15
	v_pk_fma_f32 v[16:17], v[38:39], v[4:5], v[16:17] op_sel_hi:[1,0,1]
	v_pk_fma_f32 v[12:13], v[40:41], v[4:5], v[12:13] op_sel_hi:[1,0,1]
	s_nop 0
	v_pk_add_f32 v[12:13], v[12:13], v[14:15]
	v_pk_add_f32 v[14:15], v[16:17], v[18:19]
	s_nop 0
	v_cvt_pk_bf16_f32 v14, v14, v15
	v_cvt_pk_bf16_f32 v15, v12, v13
	global_store_dwordx2 v[6:7], v[14:15], off offset:16
	v_mov_b64_e32 v[12:13], v[146:147]
	s_nop 0
	v_mov_b64_e32 v[14:15], v[162:163]
	v_lshlrev_b32_e32 v16, 16, v12
	v_and_b32_e32 v17, 0xffff0000, v12
	v_lshlrev_b32_e32 v12, 16, v13
	v_and_b32_e32 v13, 0xffff0000, v13
	v_lshlrev_b32_e32 v18, 16, v14
	v_and_b32_e32 v19, 0xffff0000, v14
	v_lshlrev_b32_e32 v14, 16, v15
	v_and_b32_e32 v15, 0xffff0000, v15
	v_pk_fma_f32 v[16:17], v[22:23], v[4:5], v[16:17] op_sel_hi:[1,0,1]
	v_pk_fma_f32 v[12:13], v[24:25], v[4:5], v[12:13] op_sel_hi:[1,0,1]
	s_nop 0
	v_pk_add_f32 v[12:13], v[12:13], v[14:15]
	v_pk_add_f32 v[14:15], v[16:17], v[18:19]
	s_nop 0
	v_cvt_pk_bf16_f32 v14, v14, v15
	v_cvt_pk_bf16_f32 v15, v12, v13
	global_store_dwordx2 v[6:7], v[14:15], off offset:80
	v_mov_b64_e32 v[12:13], v[148:149]
	s_nop 0
	v_mov_b64_e32 v[14:15], v[164:165]
	v_lshlrev_b32_e32 v16, 16, v12
	v_and_b32_e32 v17, 0xffff0000, v12
	v_lshlrev_b32_e32 v12, 16, v13
	v_and_b32_e32 v13, 0xffff0000, v13
	v_lshlrev_b32_e32 v18, 16, v14
	v_and_b32_e32 v19, 0xffff0000, v14
	v_lshlrev_b32_e32 v14, 16, v15
	v_and_b32_e32 v15, 0xffff0000, v15
	v_pk_fma_f32 v[16:17], v[42:43], v[4:5], v[16:17] op_sel_hi:[1,0,1]
	v_pk_fma_f32 v[12:13], v[44:45], v[4:5], v[12:13] op_sel_hi:[1,0,1]
	s_nop 0
	v_pk_add_f32 v[12:13], v[12:13], v[14:15]
	v_pk_add_f32 v[14:15], v[16:17], v[18:19]
	s_nop 0
	v_cvt_pk_bf16_f32 v14, v14, v15
	v_cvt_pk_bf16_f32 v15, v12, v13
	global_store_dwordx2 v[6:7], v[14:15], off offset:32
	v_mov_b64_e32 v[12:13], v[150:151]
	s_nop 0
	v_mov_b64_e32 v[14:15], v[166:167]
	v_lshlrev_b32_e32 v16, 16, v12
	v_and_b32_e32 v17, 0xffff0000, v12
	v_lshlrev_b32_e32 v12, 16, v13
	v_and_b32_e32 v13, 0xffff0000, v13
	v_lshlrev_b32_e32 v18, 16, v14
	v_and_b32_e32 v19, 0xffff0000, v14
	v_lshlrev_b32_e32 v14, 16, v15
	v_and_b32_e32 v15, 0xffff0000, v15
	v_pk_fma_f32 v[16:17], v[26:27], v[4:5], v[16:17] op_sel_hi:[1,0,1]
	v_pk_fma_f32 v[12:13], v[28:29], v[4:5], v[12:13] op_sel_hi:[1,0,1]
	s_nop 0
	v_pk_add_f32 v[12:13], v[12:13], v[14:15]
	v_pk_add_f32 v[14:15], v[16:17], v[18:19]
	s_nop 0
	v_cvt_pk_bf16_f32 v14, v14, v15
	v_cvt_pk_bf16_f32 v15, v12, v13
	global_store_dwordx2 v[6:7], v[14:15], off offset:96
	v_mov_b64_e32 v[12:13], v[152:153]
	s_nop 0
	v_mov_b64_e32 v[14:15], v[168:169]
	v_lshlrev_b32_e32 v16, 16, v12
	v_and_b32_e32 v17, 0xffff0000, v12
	v_lshlrev_b32_e32 v12, 16, v13
	v_and_b32_e32 v13, 0xffff0000, v13
	v_lshlrev_b32_e32 v18, 16, v14
	v_and_b32_e32 v19, 0xffff0000, v14
	v_lshlrev_b32_e32 v14, 16, v15
	v_and_b32_e32 v15, 0xffff0000, v15
	v_pk_fma_f32 v[16:17], v[46:47], v[4:5], v[16:17] op_sel_hi:[1,0,1]
	v_pk_fma_f32 v[12:13], v[48:49], v[4:5], v[12:13] op_sel_hi:[1,0,1]
	s_nop 0
	v_pk_add_f32 v[12:13], v[12:13], v[14:15]
	v_pk_add_f32 v[14:15], v[16:17], v[18:19]
	s_nop 0
	v_cvt_pk_bf16_f32 v14, v14, v15
	v_cvt_pk_bf16_f32 v15, v12, v13
	global_store_dwordx2 v[6:7], v[14:15], off offset:48
	v_mov_b64_e32 v[10:11], v[154:155]
	s_nop 0
	v_mov_b64_e32 v[8:9], v[170:171]
	v_lshlrev_b32_e32 v12, 16, v10
	v_and_b32_e32 v13, 0xffff0000, v10
	v_lshlrev_b32_e32 v10, 16, v11
	v_and_b32_e32 v11, 0xffff0000, v11
	v_lshlrev_b32_e32 v14, 16, v8
	v_and_b32_e32 v15, 0xffff0000, v8
	v_lshlrev_b32_e32 v8, 16, v9
	v_and_b32_e32 v9, 0xffff0000, v9
	v_pk_fma_f32 v[12:13], v[30:31], v[4:5], v[12:13] op_sel_hi:[1,0,1]
	v_pk_fma_f32 v[4:5], v[32:33], v[4:5], v[10:11] op_sel_hi:[1,0,1]
	s_nop 0
	v_pk_add_f32 v[4:5], v[4:5], v[8:9]
	v_pk_add_f32 v[8:9], v[12:13], v[14:15]
	s_nop 0
	v_cvt_pk_bf16_f32 v8, v8, v9
	v_cvt_pk_bf16_f32 v9, v4, v5
	global_store_dwordx2 v[6:7], v[8:9], off offset:112

.Lq_norepeat:
	s_and_saveexec_b64 s[64:65], s[6:7]
	v_mad_i64_i32 v[174:175], s[66:67], v22, s50, v[216:217]
	v_mad_i64_i32 v[184:185], s[66:67], v214, s50, v[216:217]
	v_or_b32_e32 v174, v174, v206
	v_or_b32_e32 v184, v184, v206
	v_lshlrev_b64 v[174:175], 1, v[174:175]
	v_lshlrev_b64 v[184:185], 1, v[184:185]
	v_lshl_add_u64 v[176:177], s[24:25], 0, v[174:175]
	v_lshl_add_u64 v[178:179], s[70:71], 0, v[174:175]
	v_lshl_add_u64 v[180:181], s[24:25], 0, v[184:185]
	v_lshl_add_u64 v[182:183], s[70:71], 0, v[184:185]
	v_lshl_add_u32 v186, v220, 1, v220
	v_mov_b64_e32 v[174:175], s[22:23]
	v_ashrrev_i32_e32 v187, 31, v186
	v_mad_i64_i32 v[188:189], s[66:67], v22, s49, v[174:175]
	v_mad_i64_i32 v[190:191], s[66:67], v214, s49, v[174:175]
	v_lshl_add_u64 v[188:189], v[186:187], 2, v[188:189]
	v_lshl_add_u64 v[190:191], v[186:187], 2, v[190:191]
	global_load_dword v172, v[188:189], off
	global_load_dwordx2 v[108:109], v[176:177], off
	global_load_dwordx2 v[124:125], v[178:179], off
	global_load_dwordx2 v[110:111], v[176:177], off offset:64
	global_load_dwordx2 v[126:127], v[178:179], off offset:64
	global_load_dwordx2 v[112:113], v[176:177], off offset:16
	global_load_dwordx2 v[128:129], v[178:179], off offset:16
	global_load_dwordx2 v[114:115], v[176:177], off offset:80
	global_load_dwordx2 v[130:131], v[178:179], off offset:80
	global_load_dwordx2 v[116:117], v[176:177], off offset:32
	global_load_dwordx2 v[132:133], v[178:179], off offset:32
	global_load_dwordx2 v[118:119], v[176:177], off offset:96
	global_load_dwordx2 v[134:135], v[178:179], off offset:96
	global_load_dwordx2 v[120:121], v[176:177], off offset:48
	global_load_dwordx2 v[136:137], v[178:179], off offset:48
	global_load_dwordx2 v[122:123], v[176:177], off offset:112
	global_load_dwordx2 v[138:139], v[178:179], off offset:112
	global_load_dword v173, v[190:191], off
	global_load_dwordx2 v[140:141], v[180:181], off
	global_load_dwordx2 v[156:157], v[182:183], off
	global_load_dwordx2 v[142:143], v[180:181], off offset:64
	global_load_dwordx2 v[158:159], v[182:183], off offset:64
	global_load_dwordx2 v[144:145], v[180:181], off offset:16
	global_load_dwordx2 v[160:161], v[182:183], off offset:16
	global_load_dwordx2 v[146:147], v[180:181], off offset:80
	global_load_dwordx2 v[162:163], v[182:183], off offset:80
	global_load_dwordx2 v[148:149], v[180:181], off offset:32
	global_load_dwordx2 v[164:165], v[182:183], off offset:32
	global_load_dwordx2 v[150:151], v[180:181], off offset:96
	global_load_dwordx2 v[166:167], v[182:183], off offset:96
	global_load_dwordx2 v[152:153], v[180:181], off offset:48
	global_load_dwordx2 v[168:169], v[182:183], off offset:48
	global_load_dwordx2 v[154:155], v[180:181], off offset:112
	global_load_dwordx2 v[170:171], v[182:183], off offset:112
	s_mov_b64 exec, s[64:65]
	s_barrier
	v_mov_b32_e32 v82, v22
	v_mad_u32_u24 v86, v226, s82, v19
	v_add_u32_e32 v87, 0x1980, v86
	v_mad_u32_u24 v88, v226, s82, v31
	v_add_u32_e32 v89, 0x1980, v88
	ds_read_b128 v[66:69], v86
	ds_read_b128 v[70:73], v86 offset:32
	ds_read_b128 v[74:77], v86 offset:64
	ds_read_b128 v[78:81], v86 offset:96
	ds_read_b128 v[50:53], v86 offset:128
	ds_read_b128 v[54:57], v86 offset:160
	ds_read_b128 v[58:61], v86 offset:192
	ds_read_b128 v[62:65], v86 offset:224
	ds_read_b32 v221, v88
	ds_read_b128 v[34:37], v87
	ds_read_b128 v[38:41], v87 offset:32
	ds_read_b128 v[42:45], v87 offset:64
	ds_read_b128 v[46:49], v87 offset:96
	ds_read_b128 v[18:21], v87 offset:128
	ds_read_b128 v[22:25], v87 offset:160
	ds_read_b128 v[26:29], v87 offset:192
	ds_read_b128 v[30:33], v87 offset:224
	ds_read_b32 v211, v89
	s_waitcnt lgkmcnt(0)
	v_mov_b32_e32 v218, v82
	v_mov_b32_e32 v102, 0
	v_mov_b32_e32 v103, 0
	v_mov_b32_e32 v104, 0
	v_mov_b32_e32 v105, 0
	ds_write_b128 v86, v[102:105]
	ds_write_b128 v86, v[102:105] offset:32
	ds_write_b128 v86, v[102:105] offset:64
	ds_write_b128 v86, v[102:105] offset:96
	ds_write_b128 v86, v[102:105] offset:128
	ds_write_b128 v86, v[102:105] offset:160
	ds_write_b128 v86, v[102:105] offset:192
	ds_write_b128 v86, v[102:105] offset:224
	ds_write_b128 v87, v[102:105]
	ds_write_b128 v87, v[102:105] offset:32
	ds_write_b128 v87, v[102:105] offset:64
	ds_write_b128 v87, v[102:105] offset:96
	ds_write_b128 v87, v[102:105] offset:128
	ds_write_b128 v87, v[102:105] offset:160
	ds_write_b128 v87, v[102:105] offset:192
	ds_write_b128 v87, v[102:105] offset:224
	ds_write_b32 v88, v102
	ds_write_b32 v89, v102
	v_mov_b32_e32 v106, 0x1800
	ds_write_b32 v106, v102
	v_lshl_add_u32 v107, v199, 2, s90
	ds_write_b32 v107, v102
.LBB0_1335:
	s_and_saveexec_b64 s[0:1], s[6:7]
	s_cbranch_execz .LBB0_1262
	ds_bpermute_b32 v2, v205, v221
	s_waitcnt vmcnt(0)
	v_lshl_add_u32 v6, v220, 1, v220
	v_mov_b32_e32 v4, 0
	v_ashrrev_i32_e32 v7, 31, v6
	s_waitcnt vmcnt(46)
	v_mov_b32_e32 v8, 0
	s_waitcnt lgkmcnt(0)
	v_add_f32_e32 v2, v221, v2
	v_cmp_lt_f32_e32 vcc, 0, v2
	s_and_saveexec_b64 s[8:9], vcc
	s_cbranch_execz .LBB0_1338
	v_mov_b64_e32 v[8:9], s[22:23]
	v_mad_i64_i32 v[8:9], s[10:11], v218, s49, v[8:9]
	v_lshl_add_u64 v[8:9], v[6:7], 2, v[8:9]
	v_mov_b32_e32 v5, v172
	v_div_scale_f32 v8, s[10:11], v2, v2, v5
	v_rcp_f32_e32 v9, v8
	v_div_scale_f32 v10, vcc, v5, v2, v5
	v_fma_f32 v11, -v8, v9, 1.0
	v_fmac_f32_e32 v9, v11, v9
	v_mul_f32_e32 v11, v10, v9
	v_fma_f32 v12, -v8, v11, v10
	v_fmac_f32_e32 v11, v12, v9
	v_fma_f32 v8, -v8, v11, v10
	v_div_fmas_f32 v8, v8, v9, v11
	v_div_fixup_f32 v8, v8, v2, v5
.LBB0_1338:
	s_or_b64 exec, exec, s[8:9]
	v_mad_i64_i32 v[10:11], s[8:9], v218, s50, v[216:217]
	v_or_b32_e32 v10, v10, v206
	v_lshlrev_b64 v[10:11], 1, v[10:11]
	v_lshl_add_u64 v[14:15], s[24:25], 0, v[10:11]
	v_mov_b64_e32 v[16:17], v[108:109]
	v_lshl_add_u64 v[12:13], s[70:71], 0, v[10:11]
	v_mov_b64_e32 v[82:83], v[124:125]
	v_lshlrev_b64 v[10:11], 11, v[218:219]
	v_lshl_add_u64 v[10:11], s[44:45], 0, v[10:11]
	v_lshlrev_b32_e32 v2, 1, v206
	v_lshl_add_u64 v[10:11], v[216:217], 1, v[10:11]
	v_lshl_add_u64 v[10:11], v[10:11], 0, v[2:3]
	ds_bpermute_b32 v5, v205, v211
	s_waitcnt lgkmcnt(0)
	v_add_f32_e32 v5, v211, v5
	v_cmp_lt_f32_e32 vcc, 0, v5
	v_lshlrev_b32_e32 v84, 16, v16
	v_and_b32_e32 v85, 0xffff0000, v16
	v_lshlrev_b32_e32 v16, 16, v17
	v_and_b32_e32 v17, 0xffff0000, v17
	v_lshlrev_b32_e32 v86, 16, v82
	v_and_b32_e32 v87, 0xffff0000, v82
	v_lshlrev_b32_e32 v82, 16, v83
	v_and_b32_e32 v83, 0xffff0000, v83
	v_pk_fma_f32 v[66:67], v[66:67], v[8:9], v[84:85] op_sel_hi:[1,0,1]
	v_pk_fma_f32 v[16:17], v[68:69], v[8:9], v[16:17] op_sel_hi:[1,0,1]
	v_pk_add_f32 v[66:67], v[66:67], v[86:87]
	v_pk_add_f32 v[16:17], v[16:17], v[82:83]
	v_cvt_pk_bf16_f32 v66, v66, v67
	v_cvt_pk_bf16_f32 v67, v16, v17
	global_store_dwordx2 v[10:11], v[66:67], off
	v_mov_b64_e32 v[16:17], v[110:111]
	s_nop 0
	v_mov_b64_e32 v[66:67], v[126:127]
	v_lshlrev_b32_e32 v68, 16, v16
	v_and_b32_e32 v69, 0xffff0000, v16
	v_lshlrev_b32_e32 v16, 16, v17
	v_and_b32_e32 v17, 0xffff0000, v17
	v_lshlrev_b32_e32 v82, 16, v66
	v_and_b32_e32 v83, 0xffff0000, v66
	v_lshlrev_b32_e32 v66, 16, v67
	v_and_b32_e32 v67, 0xffff0000, v67
	v_pk_fma_f32 v[50:51], v[50:51], v[8:9], v[68:69] op_sel_hi:[1,0,1]
	v_pk_fma_f32 v[16:17], v[52:53], v[8:9], v[16:17] op_sel_hi:[1,0,1]
	v_pk_add_f32 v[50:51], v[50:51], v[82:83]
	v_pk_add_f32 v[16:17], v[16:17], v[66:67]
	v_cvt_pk_bf16_f32 v50, v50, v51
	v_cvt_pk_bf16_f32 v51, v16, v17
	global_store_dwordx2 v[10:11], v[50:51], off offset:64
	v_mov_b64_e32 v[16:17], v[112:113]
	s_nop 0
	v_mov_b64_e32 v[50:51], v[128:129]
	v_lshlrev_b32_e32 v52, 16, v16
	v_and_b32_e32 v53, 0xffff0000, v16
	v_lshlrev_b32_e32 v16, 16, v17
	v_and_b32_e32 v17, 0xffff0000, v17
	v_lshlrev_b32_e32 v66, 16, v50
	v_and_b32_e32 v67, 0xffff0000, v50
	v_lshlrev_b32_e32 v50, 16, v51
	v_and_b32_e32 v51, 0xffff0000, v51
	v_pk_fma_f32 v[52:53], v[70:71], v[8:9], v[52:53] op_sel_hi:[1,0,1]
	v_pk_fma_f32 v[16:17], v[72:73], v[8:9], v[16:17] op_sel_hi:[1,0,1]
	s_nop 0
	v_pk_add_f32 v[16:17], v[16:17], v[50:51]
	v_pk_add_f32 v[50:51], v[52:53], v[66:67]
	s_nop 0
	v_cvt_pk_bf16_f32 v50, v50, v51
	v_cvt_pk_bf16_f32 v51, v16, v17
	global_store_dwordx2 v[10:11], v[50:51], off offset:16
	v_mov_b64_e32 v[16:17], v[114:115]
	s_nop 0
	v_mov_b64_e32 v[50:51], v[130:131]
	v_lshlrev_b32_e32 v52, 16, v16
	v_and_b32_e32 v53, 0xffff0000, v16
	v_lshlrev_b32_e32 v16, 16, v17
	v_and_b32_e32 v17, 0xffff0000, v17
	v_lshlrev_b32_e32 v66, 16, v50
	v_and_b32_e32 v67, 0xffff0000, v50
	v_lshlrev_b32_e32 v50, 16, v51
	v_and_b32_e32 v51, 0xffff0000, v51
	v_pk_fma_f32 v[52:53], v[54:55], v[8:9], v[52:53] op_sel_hi:[1,0,1]
	v_pk_fma_f32 v[16:17], v[56:57], v[8:9], v[16:17] op_sel_hi:[1,0,1]
	s_nop 0
	v_pk_add_f32 v[16:17], v[16:17], v[50:51]
	v_pk_add_f32 v[50:51], v[52:53], v[66:67]
	s_nop 0
	v_cvt_pk_bf16_f32 v50, v50, v51
	v_cvt_pk_bf16_f32 v51, v16, v17
	global_store_dwordx2 v[10:11], v[50:51], off offset:80
	v_mov_b64_e32 v[16:17], v[116:117]
	s_nop 0
	v_mov_b64_e32 v[50:51], v[132:133]
	v_lshlrev_b32_e32 v52, 16, v16
	v_and_b32_e32 v53, 0xffff0000, v16
	v_lshlrev_b32_e32 v16, 16, v17
	v_and_b32_e32 v17, 0xffff0000, v17
	v_lshlrev_b32_e32 v54, 16, v50
	v_and_b32_e32 v55, 0xffff0000, v50
	v_lshlrev_b32_e32 v50, 16, v51
	v_and_b32_e32 v51, 0xffff0000, v51
	v_pk_fma_f32 v[52:53], v[74:75], v[8:9], v[52:53] op_sel_hi:[1,0,1]
	v_pk_fma_f32 v[16:17], v[76:77], v[8:9], v[16:17] op_sel_hi:[1,0,1]
	s_nop 0
	v_pk_add_f32 v[16:17], v[16:17], v[50:51]
	v_pk_add_f32 v[50:51], v[52:53], v[54:55]
	s_nop 0
	v_cvt_pk_bf16_f32 v50, v50, v51
	v_cvt_pk_bf16_f32 v51, v16, v17
	global_store_dwordx2 v[10:11], v[50:51], off offset:32
	v_mov_b64_e32 v[16:17], v[118:119]
	s_nop 0
	v_mov_b64_e32 v[50:51], v[134:135]
	v_lshlrev_b32_e32 v52, 16, v16
	v_and_b32_e32 v53, 0xffff0000, v16
	v_lshlrev_b32_e32 v16, 16, v17
	v_and_b32_e32 v17, 0xffff0000, v17
	v_lshlrev_b32_e32 v54, 16, v50
	v_and_b32_e32 v55, 0xffff0000, v50
	v_lshlrev_b32_e32 v50, 16, v51
	v_and_b32_e32 v51, 0xffff0000, v51
	v_pk_fma_f32 v[52:53], v[58:59], v[8:9], v[52:53] op_sel_hi:[1,0,1]
	v_pk_fma_f32 v[16:17], v[60:61], v[8:9], v[16:17] op_sel_hi:[1,0,1]
	s_nop 0
	v_pk_add_f32 v[16:17], v[16:17], v[50:51]
	v_pk_add_f32 v[50:51], v[52:53], v[54:55]
	s_nop 0
	v_cvt_pk_bf16_f32 v50, v50, v51
	v_cvt_pk_bf16_f32 v51, v16, v17
	global_store_dwordx2 v[10:11], v[50:51], off offset:96
	v_mov_b64_e32 v[16:17], v[120:121]
	s_nop 0
	v_mov_b64_e32 v[50:51], v[136:137]
	v_lshlrev_b32_e32 v52, 16, v16
	v_and_b32_e32 v53, 0xffff0000, v16
	v_lshlrev_b32_e32 v16, 16, v17
	v_and_b32_e32 v17, 0xffff0000, v17
	v_lshlrev_b32_e32 v54, 16, v50
	v_and_b32_e32 v55, 0xffff0000, v50
	v_lshlrev_b32_e32 v50, 16, v51
	v_and_b32_e32 v51, 0xffff0000, v51
	v_pk_fma_f32 v[52:53], v[78:79], v[8:9], v[52:53] op_sel_hi:[1,0,1]
	v_pk_fma_f32 v[16:17], v[80:81], v[8:9], v[16:17] op_sel_hi:[1,0,1]
	s_nop 0
	v_pk_add_f32 v[16:17], v[16:17], v[50:51]
	v_pk_add_f32 v[50:51], v[52:53], v[54:55]
	s_nop 0
	v_cvt_pk_bf16_f32 v50, v50, v51
	v_cvt_pk_bf16_f32 v51, v16, v17
	global_store_dwordx2 v[10:11], v[50:51], off offset:48
	v_mov_b64_e32 v[14:15], v[122:123]
	s_nop 0
	v_mov_b64_e32 v[12:13], v[138:139]
	v_lshlrev_b32_e32 v16, 16, v14
	v_and_b32_e32 v17, 0xffff0000, v14
	v_lshlrev_b32_e32 v14, 16, v15
	v_and_b32_e32 v15, 0xffff0000, v15
	v_lshlrev_b32_e32 v50, 16, v12
	v_and_b32_e32 v51, 0xffff0000, v12
	v_lshlrev_b32_e32 v12, 16, v13
	v_and_b32_e32 v13, 0xffff0000, v13
	v_pk_fma_f32 v[16:17], v[62:63], v[8:9], v[16:17] op_sel_hi:[1,0,1]
	v_pk_fma_f32 v[8:9], v[64:65], v[8:9], v[14:15] op_sel_hi:[1,0,1]
	s_nop 0
	v_pk_add_f32 v[8:9], v[8:9], v[12:13]
	v_pk_add_f32 v[12:13], v[16:17], v[50:51]
	s_nop 0
	v_cvt_pk_bf16_f32 v12, v12, v13
	v_cvt_pk_bf16_f32 v13, v8, v9
	global_store_dwordx2 v[10:11], v[12:13], off offset:112
	s_and_saveexec_b64 s[8:9], vcc
	s_cbranch_execz .LBB0_1261
	v_mov_b64_e32 v[8:9], s[22:23]
	v_mad_i64_i32 v[8:9], s[10:11], v214, s49, v[8:9]
	v_lshl_add_u64 v[6:7], v[6:7], 2, v[8:9]
	v_mov_b32_e32 v4, v173
	v_div_scale_f32 v6, s[10:11], v5, v5, v4
	v_rcp_f32_e32 v7, v6
	v_div_scale_f32 v8, vcc, v4, v5, v4
	v_fma_f32 v9, -v6, v7, 1.0
	v_fmac_f32_e32 v7, v9, v7
	v_mul_f32_e32 v9, v8, v7
	v_fma_f32 v10, -v6, v9, v8
	v_fmac_f32_e32 v9, v10, v7
	v_fma_f32 v6, -v6, v9, v8
	v_div_fmas_f32 v6, v6, v7, v9
	v_div_fixup_f32 v4, v6, v5, v4
	s_branch .LBB0_1261
